# v58 + MLP1 relu^2 epilogue: canonicalize+relu pairs (2 v_max) folded into one v_max3_f32 x,x,0 (bit-identical), store-data hazard distance kept with s_nop
# speedup vs baseline: 1.0181x; 1.0022x over previous
; __device__ __forceinline__ unsigned cvt_pk_bf16(float lo, float hi) { unsigned r; asm volatile("v_cvt_pk_bf16_f32 %0, %1, %2" : "=v"(r) : "v"(lo), "v"(hi)); return r; }
; #define PG8_OPQ(p) asm volatile("" : "+v"(p))
;     __device__ __forceinline__ void operator()(const f32x4 (&acc)[2][2][4][2], const Unit& u, int wr, int wc, int fr, int fq) const {
;     ...
;             for (int m = 0; m < 4; ++m) {
;                 PG8_OPQ(p);
; #pragma unroll
;                 for (int bj = 0; bj < 2; ++bj) { f32x4 v0 = acc[ai][bj][m][0], v1 = acc[ai][bj][m][1];
;                     if (ACT == 1) {
; #pragma unroll
;                         for (int j = 0; j < 4; ++j) { const float a0 = fmaxf(v0[j], 0.f), a1 = fmaxf(v1[j], 0.f); v0[j] = a0 * a0; v1[j] = a1 * a1; } }
;                     u32x4 w; w.x = cvt_pk_bf16(v0[0], v0[1]); w.y = cvt_pk_bf16(v0[2], v0[3]); w.z = cvt_pk_bf16(v1[0], v1[1]); w.w = cvt_pk_bf16(v1[2], v1[3]);
;                     *(u32x4*)(p + bj * HALF * 2) = w; }
;                 p += step;
.LBB0_438:
	v_max3_f32 v122, v122, v122, 0
	s_lshr_b32 s36, s8, 2
	s_lshl_b32 s36, s36, 23
	s_and_b32 s99, s8, 3
	s_lshl_b32 s99, s99, 8
	s_add_u32 s36, s36, s99
	s_lshr_b32 s99, s98, 14
	s_add_u32 s36, s36, s99
	v_max3_f32 v123, v123, v123, 0
	v_max3_f32 v124, v124, v124, 0
	v_max3_f32 v125, v125, v125, 0
	v_lshl_add_u64 v[144:145], s[36:37], 1, v[136:137]
	v_max3_f32 v126, v126, v126, 0
	v_mul_f32_e32 v122, v122, v122
	v_max3_f32 v127, v127, v127, 0
	v_max3_f32 v128, v128, v128, 0
	v_max3_f32 v129, v129, v129, 0
	v_max3_f32 v114, v114, v114, 0
	v_max3_f32 v115, v115, v115, 0
	v_max3_f32 v116, v116, v116, 0
	v_mul_f32_e32 v123, v123, v123
	v_mul_f32_e32 v124, v124, v124
	v_mul_f32_e32 v125, v125, v125
	v_cvt_pk_bf16_f32 v122, v122, v123
	v_mul_f32_e32 v126, v126, v126
	v_mul_f32_e32 v127, v127, v127
	v_mul_f32_e32 v128, v128, v128
	v_mul_f32_e32 v129, v129, v129
	v_cvt_pk_bf16_f32 v123, v124, v125
	v_cvt_pk_bf16_f32 v124, v126, v127
	v_cvt_pk_bf16_f32 v125, v128, v129
	global_store_dwordx4 v[144:145], v[122:125], off
	v_max3_f32 v118, v118, v118, 0
	v_max3_f32 v117, v117, v117, 0
	v_mul_f32_e32 v122, v114, v114
	v_max3_f32 v114, v119, v119, 0
	v_mul_f32_e32 v119, v115, v115
	v_max3_f32 v115, v120, v120, 0
	v_mul_f32_e32 v120, v116, v116
	v_max3_f32 v116, v121, v121, 0
	v_mul_f32_e32 v114, v114, v114
	v_mul_f32_e32 v115, v115, v115
	v_mul_f32_e32 v116, v116, v116
	v_max3_f32 v106, v106, v106, 0
	v_mul_f32_e32 v118, v118, v118
	v_mul_f32_e32 v117, v117, v117
	v_cvt_pk_bf16_f32 v114, v118, v114
	v_cvt_pk_bf16_f32 v115, v115, v116
	v_cvt_pk_bf16_f32 v116, v122, v119
	v_max3_f32 v107, v107, v107, 0
	v_max3_f32 v108, v108, v108, 0
	v_cvt_pk_bf16_f32 v117, v120, v117
	global_store_dwordx4 v[144:145], v[114:117], off offset:256
	s_nop 1
	v_mul_f32_e32 v116, v106, v106
	v_max3_f32 v106, v111, v111, 0
	v_max3_f32 v110, v110, v110, 0
	v_mul_f32_e32 v111, v107, v107
	v_max3_f32 v107, v112, v112, 0
	v_mul_f32_e32 v112, v108, v108
	v_max3_f32 v108, v113, v113, 0
	v_max3_f32 v109, v109, v109, 0
	v_lshl_add_u64 v[114:115], v[144:145], 0, s[16:17]
	v_mul_f32_e32 v106, v106, v106
	v_max3_f32 v98, v98, v98, 0
	v_max3_f32 v99, v99, v99, 0
	v_max3_f32 v100, v100, v100, 0
	v_mul_f32_e32 v110, v110, v110
	v_mul_f32_e32 v107, v107, v107
	v_mul_f32_e32 v108, v108, v108
	v_mul_f32_e32 v109, v109, v109
	v_cvt_pk_bf16_f32 v106, v110, v106
	v_cvt_pk_bf16_f32 v107, v107, v108
	v_cvt_pk_bf16_f32 v108, v116, v111
	v_cvt_pk_bf16_f32 v109, v112, v109
	global_store_dwordx4 v[114:115], v[106:109], off
	v_max3_f32 v102, v102, v102, 0
	v_max3_f32 v101, v101, v101, 0
	v_mul_f32_e32 v106, v98, v98
	v_max3_f32 v98, v103, v103, 0
	v_mul_f32_e32 v103, v99, v99
	v_max3_f32 v99, v104, v104, 0
	v_mul_f32_e32 v104, v100, v100
	v_max3_f32 v100, v105, v105, 0
	v_mul_f32_e32 v98, v98, v98
	v_mul_f32_e32 v99, v99, v99
	v_mul_f32_e32 v100, v100, v100
	v_max3_f32 v90, v90, v90, 0
	v_mul_f32_e32 v102, v102, v102
	v_mul_f32_e32 v101, v101, v101
	v_cvt_pk_bf16_f32 v98, v102, v98
	v_cvt_pk_bf16_f32 v99, v99, v100
	v_cvt_pk_bf16_f32 v100, v106, v103
	v_max3_f32 v91, v91, v91, 0
	v_max3_f32 v92, v92, v92, 0
	v_cvt_pk_bf16_f32 v101, v104, v101
	global_store_dwordx4 v[114:115], v[98:101], off offset:256
	s_nop 1
	v_mul_f32_e32 v100, v90, v90
	v_max3_f32 v90, v95, v95, 0
	v_max3_f32 v94, v94, v94, 0
	v_mul_f32_e32 v95, v91, v91
	v_max3_f32 v91, v96, v96, 0
	v_mul_f32_e32 v96, v92, v92
	v_max3_f32 v92, v97, v97, 0
	v_max3_f32 v93, v93, v93, 0
	v_lshl_add_u64 v[98:99], v[114:115], 0, s[16:17]
	v_mul_f32_e32 v90, v90, v90
	v_max3_f32 v82, v82, v82, 0
	v_max3_f32 v83, v83, v83, 0
	v_max3_f32 v84, v84, v84, 0
	v_mul_f32_e32 v94, v94, v94
	v_mul_f32_e32 v91, v91, v91
	v_mul_f32_e32 v92, v92, v92
	v_mul_f32_e32 v93, v93, v93
	v_cvt_pk_bf16_f32 v90, v94, v90
	v_cvt_pk_bf16_f32 v91, v91, v92
	v_cvt_pk_bf16_f32 v92, v100, v95
	v_cvt_pk_bf16_f32 v93, v96, v93
	global_store_dwordx4 v[98:99], v[90:93], off
	v_max3_f32 v86, v86, v86, 0
	v_max3_f32 v85, v85, v85, 0
	v_mul_f32_e32 v90, v82, v82
	v_max3_f32 v82, v87, v87, 0
	v_mul_f32_e32 v87, v83, v83
	v_max3_f32 v83, v88, v88, 0
	v_mul_f32_e32 v88, v84, v84
	v_max3_f32 v84, v89, v89, 0
	v_mul_f32_e32 v82, v82, v82
	v_mul_f32_e32 v83, v83, v83
	v_mul_f32_e32 v84, v84, v84
	v_max3_f32 v74, v74, v74, 0
	v_mul_f32_e32 v86, v86, v86
	v_mul_f32_e32 v85, v85, v85
	v_cvt_pk_bf16_f32 v82, v86, v82
	v_cvt_pk_bf16_f32 v83, v83, v84
	v_cvt_pk_bf16_f32 v84, v90, v87
	v_max3_f32 v75, v75, v75, 0
	v_max3_f32 v76, v76, v76, 0
	v_cvt_pk_bf16_f32 v85, v88, v85
	global_store_dwordx4 v[98:99], v[82:85], off offset:256
	s_nop 1
	v_mul_f32_e32 v84, v74, v74
	v_max3_f32 v74, v79, v79, 0
	v_max3_f32 v78, v78, v78, 0
	v_mul_f32_e32 v79, v75, v75
	v_max3_f32 v75, v80, v80, 0
	v_mul_f32_e32 v80, v76, v76
	v_max3_f32 v76, v81, v81, 0
	v_max3_f32 v77, v77, v77, 0
	v_lshl_add_u64 v[82:83], v[98:99], 0, s[16:17]
	v_mul_f32_e32 v74, v74, v74
	v_max3_f32 v66, v66, v66, 0
	v_max3_f32 v67, v67, v67, 0
	v_max3_f32 v68, v68, v68, 0
	v_mul_f32_e32 v78, v78, v78
	v_mul_f32_e32 v75, v75, v75
	v_mul_f32_e32 v76, v76, v76
	v_mul_f32_e32 v77, v77, v77
	v_cvt_pk_bf16_f32 v74, v78, v74
	v_cvt_pk_bf16_f32 v75, v75, v76
	v_cvt_pk_bf16_f32 v76, v84, v79
	v_cvt_pk_bf16_f32 v77, v80, v77
	global_store_dwordx4 v[82:83], v[74:77], off
	v_max3_f32 v70, v70, v70, 0
	v_max3_f32 v69, v69, v69, 0
	v_mul_f32_e32 v74, v66, v66
	v_max3_f32 v66, v71, v71, 0
	v_mul_f32_e32 v71, v67, v67
	v_max3_f32 v67, v72, v72, 0
	v_mul_f32_e32 v72, v68, v68
	v_max3_f32 v68, v73, v73, 0
	v_mul_f32_e32 v66, v66, v66
	v_mul_f32_e32 v67, v67, v67
	v_mul_f32_e32 v68, v68, v68
	v_max3_f32 v58, v58, v58, 0
	v_mul_f32_e32 v70, v70, v70
; __device__ __forceinline__ unsigned cvt_pk_bf16(float lo, float hi) { unsigned r; asm volatile("v_cvt_pk_bf16_f32 %0, %1, %2" : "=v"(r) : "v"(lo), "v"(hi)); return r; }
; #define PG8_OPQ(p) asm volatile("" : "+v"(p))
;     __device__ __forceinline__ void operator()(const f32x4 (&acc)[2][2][4][2], const Unit& u, int wr, int wc, int fr, int fq) const {
;     ...
;             for (int m = 0; m < 4; ++m) {
;                 PG8_OPQ(p);
; #pragma unroll
;                 for (int bj = 0; bj < 2; ++bj) { f32x4 v0 = acc[ai][bj][m][0], v1 = acc[ai][bj][m][1];
;                     if (ACT == 1) {
; #pragma unroll
;                         for (int j = 0; j < 4; ++j) { const float a0 = fmaxf(v0[j], 0.f), a1 = fmaxf(v1[j], 0.f); v0[j] = a0 * a0; v1[j] = a1 * a1; } }
;                     u32x4 w; w.x = cvt_pk_bf16(v0[0], v0[1]); w.y = cvt_pk_bf16(v0[2], v0[3]); w.z = cvt_pk_bf16(v1[0], v1[1]); w.w = cvt_pk_bf16(v1[2], v1[3]);
;                     *(u32x4*)(p + bj * HALF * 2) = w; }
;                 p += step;
	v_mul_f32_e32 v69, v69, v69
	v_cvt_pk_bf16_f32 v66, v70, v66
	v_cvt_pk_bf16_f32 v67, v67, v68
	v_cvt_pk_bf16_f32 v68, v74, v71
	v_max3_f32 v59, v59, v59, 0
	v_max3_f32 v60, v60, v60, 0
	v_cvt_pk_bf16_f32 v69, v72, v69
	global_store_dwordx4 v[82:83], v[66:69], off offset:256
	s_nop 1
	v_mul_f32_e32 v68, v58, v58
	v_max3_f32 v58, v63, v63, 0
	s_mov_b64 s[48:49], 0xa0000
	v_max3_f32 v62, v62, v62, 0
	v_mul_f32_e32 v63, v59, v59
	v_max3_f32 v59, v64, v64, 0
	v_mul_f32_e32 v64, v60, v60
	v_max3_f32 v60, v65, v65, 0
	v_max3_f32 v61, v61, v61, 0
	v_lshl_add_u64 v[66:67], v[82:83], 0, s[48:49]
	v_mul_f32_e32 v58, v58, v58
	v_max3_f32 v50, v50, v50, 0
	v_max3_f32 v51, v51, v51, 0
	v_max3_f32 v52, v52, v52, 0
	v_mul_f32_e32 v62, v62, v62
	v_mul_f32_e32 v59, v59, v59
	v_mul_f32_e32 v60, v60, v60
	v_mul_f32_e32 v61, v61, v61
	v_cvt_pk_bf16_f32 v58, v62, v58
	v_cvt_pk_bf16_f32 v59, v59, v60
	v_cvt_pk_bf16_f32 v60, v68, v63
	v_cvt_pk_bf16_f32 v61, v64, v61
	global_store_dwordx4 v[66:67], v[58:61], off
	v_max3_f32 v54, v54, v54, 0
	v_max3_f32 v53, v53, v53, 0
	v_mul_f32_e32 v58, v50, v50
	v_max3_f32 v50, v55, v55, 0
	v_mul_f32_e32 v55, v51, v51
	v_max3_f32 v51, v56, v56, 0
	v_mul_f32_e32 v56, v52, v52
	v_max3_f32 v52, v57, v57, 0
	v_mul_f32_e32 v50, v50, v50
	v_mul_f32_e32 v51, v51, v51
	v_mul_f32_e32 v52, v52, v52
	v_max3_f32 v42, v42, v42, 0
	v_mul_f32_e32 v54, v54, v54
	v_mul_f32_e32 v53, v53, v53
	v_cvt_pk_bf16_f32 v50, v54, v50
	v_cvt_pk_bf16_f32 v51, v51, v52
	v_cvt_pk_bf16_f32 v52, v58, v55
	v_max3_f32 v43, v43, v43, 0
	v_max3_f32 v44, v44, v44, 0
	v_cvt_pk_bf16_f32 v53, v56, v53
	global_store_dwordx4 v[66:67], v[50:53], off offset:256
	s_nop 1
	v_mul_f32_e32 v52, v42, v42
	v_max3_f32 v42, v47, v47, 0
	v_max3_f32 v46, v46, v46, 0
	v_mul_f32_e32 v47, v43, v43
	v_max3_f32 v43, v48, v48, 0
	v_mul_f32_e32 v48, v44, v44
	v_max3_f32 v44, v49, v49, 0
	v_max3_f32 v45, v45, v45, 0
	v_lshl_add_u64 v[50:51], v[66:67], 0, s[16:17]
	v_mul_f32_e32 v42, v42, v42
	v_max3_f32 v34, v34, v34, 0
	v_max3_f32 v35, v35, v35, 0
	v_max3_f32 v36, v36, v36, 0
	v_mul_f32_e32 v46, v46, v46
	v_mul_f32_e32 v43, v43, v43
	v_mul_f32_e32 v44, v44, v44
	v_mul_f32_e32 v45, v45, v45
	v_cvt_pk_bf16_f32 v42, v46, v42
	v_cvt_pk_bf16_f32 v43, v43, v44
	v_cvt_pk_bf16_f32 v44, v52, v47
	v_cvt_pk_bf16_f32 v45, v48, v45
	global_store_dwordx4 v[50:51], v[42:45], off
	v_max3_f32 v38, v38, v38, 0
	v_max3_f32 v37, v37, v37, 0
	v_mul_f32_e32 v42, v34, v34
	v_max3_f32 v34, v39, v39, 0
	v_mul_f32_e32 v39, v35, v35
	v_max3_f32 v35, v40, v40, 0
	v_mul_f32_e32 v40, v36, v36
	v_max3_f32 v36, v41, v41, 0
	v_mul_f32_e32 v34, v34, v34
	v_mul_f32_e32 v35, v35, v35
	v_mul_f32_e32 v36, v36, v36
	v_max3_f32 v26, v26, v26, 0
	v_mul_f32_e32 v38, v38, v38
	v_mul_f32_e32 v37, v37, v37
	v_cvt_pk_bf16_f32 v34, v38, v34
	v_cvt_pk_bf16_f32 v35, v35, v36
	v_cvt_pk_bf16_f32 v36, v42, v39
	v_max3_f32 v27, v27, v27, 0
	v_max3_f32 v28, v28, v28, 0
	v_cvt_pk_bf16_f32 v37, v40, v37
	global_store_dwordx4 v[50:51], v[34:37], off offset:256
	s_nop 1
	v_mul_f32_e32 v36, v26, v26
	v_max3_f32 v26, v31, v31, 0
	v_max3_f32 v30, v30, v30, 0
	v_mul_f32_e32 v31, v27, v27
	v_max3_f32 v27, v32, v32, 0
	v_mul_f32_e32 v32, v28, v28
	v_max3_f32 v28, v33, v33, 0
	v_max3_f32 v29, v29, v29, 0
	v_lshl_add_u64 v[34:35], v[50:51], 0, s[16:17]
	v_mul_f32_e32 v26, v26, v26
	v_max3_f32 v18, v18, v18, 0
	v_max3_f32 v19, v19, v19, 0
	v_max3_f32 v20, v20, v20, 0
	v_mul_f32_e32 v30, v30, v30
	v_mul_f32_e32 v27, v27, v27
	v_mul_f32_e32 v28, v28, v28
	v_mul_f32_e32 v29, v29, v29
	v_cvt_pk_bf16_f32 v26, v30, v26
	v_cvt_pk_bf16_f32 v27, v27, v28
	v_cvt_pk_bf16_f32 v28, v36, v31
	v_cvt_pk_bf16_f32 v29, v32, v29
	global_store_dwordx4 v[34:35], v[26:29], off
	v_max3_f32 v22, v22, v22, 0
	v_max3_f32 v21, v21, v21, 0
	v_mul_f32_e32 v26, v18, v18
	v_max3_f32 v18, v23, v23, 0
	v_mul_f32_e32 v23, v19, v19
	v_max3_f32 v19, v24, v24, 0
	v_mul_f32_e32 v24, v20, v20
	v_max3_f32 v20, v25, v25, 0
	v_mul_f32_e32 v18, v18, v18
	v_mul_f32_e32 v19, v19, v19
	v_mul_f32_e32 v20, v20, v20
	v_max3_f32 v10, v10, v10, 0
	v_mul_f32_e32 v22, v22, v22
	v_mul_f32_e32 v21, v21, v21
	v_cvt_pk_bf16_f32 v18, v22, v18
	v_cvt_pk_bf16_f32 v19, v19, v20
	v_cvt_pk_bf16_f32 v20, v26, v23
	v_max3_f32 v11, v11, v11, 0
	v_max3_f32 v12, v12, v12, 0
	v_cvt_pk_bf16_f32 v21, v24, v21
	global_store_dwordx4 v[34:35], v[18:21], off offset:256
	s_nop 1
	v_mul_f32_e32 v20, v10, v10
	v_max3_f32 v10, v15, v15, 0
	v_max3_f32 v14, v14, v14, 0
	v_mul_f32_e32 v15, v11, v11
	v_max3_f32 v11, v16, v16, 0
	v_mul_f32_e32 v16, v12, v12
	v_max3_f32 v12, v17, v17, 0
	v_max3_f32 v13, v13, v13, 0
	v_lshl_add_u64 v[18:19], v[34:35], 0, s[16:17]
	v_mul_f32_e32 v10, v10, v10
	v_max3_f32 v2, v2, v2, 0
	v_max3_f32 v3, v3, v3, 0
	v_max3_f32 v4, v4, v4, 0
	v_mul_f32_e32 v14, v14, v14
	v_mul_f32_e32 v11, v11, v11
	v_mul_f32_e32 v12, v12, v12
	v_mul_f32_e32 v13, v13, v13
	v_cvt_pk_bf16_f32 v10, v14, v10
	v_cvt_pk_bf16_f32 v11, v11, v12
	v_cvt_pk_bf16_f32 v12, v20, v15
	v_cvt_pk_bf16_f32 v13, v16, v13
	global_store_dwordx4 v[18:19], v[10:13], off
	v_max3_f32 v5, v5, v5, 0
	v_max3_f32 v6, v6, v6, 0
	v_mul_f32_e32 v10, v2, v2
	v_max3_f32 v2, v7, v7, 0
	v_mul_f32_e32 v7, v3, v3
	v_max3_f32 v3, v8, v8, 0
	v_mul_f32_e32 v8, v4, v4
	v_max3_f32 v4, v9, v9, 0
	v_mul_f32_e32 v2, v2, v2
	v_mul_f32_e32 v3, v3, v3
	v_mul_f32_e32 v4, v4, v4
	v_mul_f32_e32 v5, v5, v5
	s_cmp_eq_u32 s8, 15
	s_mov_b64 s[8:9], -1
	v_mul_f32_e32 v6, v6, v6
	v_cvt_pk_bf16_f32 v2, v6, v2
	v_cvt_pk_bf16_f32 v3, v3, v4
	v_cvt_pk_bf16_f32 v4, v10, v7
	v_cvt_pk_bf16_f32 v5, v8, v5
	global_store_dwordx4 v[18:19], v[2:5], off offset:256
	s_cbranch_scc1 .LBB0_430
	s_andn2_b64 vcc, exec, s[38:39]
	s_cbranch_vccnz .LBB0_429
	s_barrier
	s_branch .LBB0_429
